# grid barrier: all workgroups poll the top-level generation word directly (per-XCD re-publication dropped)
# speedup vs baseline: 1.0264x; 1.0037x over previous
.LBB0_68:
	s_or_b64 exec, exec, s[10:11]
	v_cvt_f32_u32_e32 v5, v3
	s_waitcnt vmcnt(0)
	v_readfirstlane_b32 s3, v4
	v_sub_u32_e32 v4, 0, v3
	v_rcp_iflag_f32_e32 v5, v5
	v_add_u32_e32 v6, s3, v2
	v_mul_f32_e32 v5, 0x4f7ffffe, v5
	v_cvt_u32_f32_e32 v5, v5
	v_mul_lo_u32 v2, v4, v5
	v_mul_hi_u32 v2, v5, v2
	v_add_u32_e32 v2, v5, v2
	v_mul_hi_u32 v2, v6, v2
	v_mul_lo_u32 v4, v2, v3
	v_sub_u32_e32 v4, v6, v4
	v_add_u32_e32 v5, 1, v2
	v_cmp_ge_u32_e32 vcc, v4, v3
	s_nop 1
	v_cndmask_b32_e32 v2, v2, v5, vcc
	v_sub_u32_e32 v5, v4, v3
	v_cndmask_b32_e32 v4, v4, v5, vcc
	v_add_u32_e32 v5, 1, v2
	v_cmp_ge_u32_e32 vcc, v4, v3
	v_add_u32_e32 v4, 1, v6
	s_nop 0
	v_cndmask_b32_e32 v2, v2, v5, vcc
	v_mul_lo_u32 v5, v3, v2
	v_add_u32_e32 v3, v5, v3
	v_cmp_ne_u32_e32 vcc, v4, v3
	s_and_saveexec_b64 s[8:9], vcc
	s_xor_b64 s[8:9], exec, s[8:9]
	s_cbranch_execz .LBB0_82
	s_waitcnt lgkmcnt(0)
	v_mov_b32_e32 v1, 0x23903500
	global_load_dword v1, v1, s[26:27] sc1
	s_add_u32 s14, s26, 0x23903500
	s_addc_u32 s15, s27, 0
	s_waitcnt vmcnt(0)
	v_cmp_eq_u32_e32 vcc, v1, v2
	s_and_saveexec_b64 s[10:11], vcc
	s_cbranch_execz .LBB0_81
	s_add_u32 s12, s26, 0x23900200
	s_addc_u32 s13, s27, 0
	s_mov_b32 s3, 1
	s_mov_b64 s[16:17], 0
	v_mov_b32_e32 v1, 0
	s_branch .LBB0_72

.LBB0_99:
	s_or_b64 exec, exec, s[8:9]
	s_mov_b64 s[8:9], exec
	v_mbcnt_lo_u32_b32 v1, s8, 0
	v_mbcnt_hi_u32_b32 v1, s9, v1
	v_cmp_eq_u32_e32 vcc, 0, v1
	s_waitcnt vmcnt(0)
	buffer_inv sc1
	s_and_saveexec_b64 s[10:11], vcc
	s_cbranch_execz .LBB0_101
	s_bcnt1_i32_b64 s3, s[8:9]
	v_mov_b32_e32 v1, 0x2000
	v_mov_b32_e32 v2, s3
.LBB0_101:
	s_or_b64 exec, exec, s[10:11]
	s_waitcnt vmcnt(0)

.LBB0_235:
	s_or_b64 exec, exec, s[8:9]
	s_mov_b64 s[8:9], exec
	v_mbcnt_lo_u32_b32 v1, s8, 0
	v_mbcnt_hi_u32_b32 v1, s9, v1
	v_cmp_eq_u32_e32 vcc, 0, v1
	s_waitcnt vmcnt(0)
	buffer_inv sc1
	s_and_saveexec_b64 s[10:11], vcc
	s_cbranch_execz .LBB0_237
	s_bcnt1_i32_b64 s3, s[8:9]
	v_mov_b32_e32 v1, 0x2000
	v_mov_b32_e32 v2, s3
.LBB0_237:
	s_or_b64 exec, exec, s[10:11]
	s_waitcnt vmcnt(0)

.LBB0_305:
	s_or_b64 exec, exec, s[8:9]
	s_mov_b64 s[8:9], exec
	v_mbcnt_lo_u32_b32 v1, s8, 0
	v_mbcnt_hi_u32_b32 v1, s9, v1
	v_cmp_eq_u32_e32 vcc, 0, v1
	s_waitcnt vmcnt(0)
	buffer_inv sc1
	s_and_saveexec_b64 s[10:11], vcc
	s_cbranch_execz .LBB0_307
	s_bcnt1_i32_b64 s3, s[8:9]
	v_mov_b32_e32 v1, 0x2000
	v_mov_b32_e32 v2, s3
.LBB0_307:
	s_or_b64 exec, exec, s[10:11]
	s_waitcnt vmcnt(0)

.LBB0_393:
	s_or_b64 exec, exec, s[8:9]
	s_mov_b64 s[8:9], exec
	v_mbcnt_lo_u32_b32 v1, s8, 0
	v_mbcnt_hi_u32_b32 v1, s9, v1
	v_cmp_eq_u32_e32 vcc, 0, v1
	s_waitcnt vmcnt(0)
	buffer_inv sc1
	s_and_saveexec_b64 s[10:11], vcc
	s_cbranch_execz .LBB0_395
	s_bcnt1_i32_b64 s3, s[8:9]
	v_mov_b32_e32 v1, 0x2000
	v_mov_b32_e32 v2, s3
.LBB0_395:
	s_or_b64 exec, exec, s[10:11]
	s_waitcnt vmcnt(0)

.LBB0_486:
	s_or_b64 exec, exec, s[8:9]
	s_mov_b64 s[8:9], exec
	v_mbcnt_lo_u32_b32 v1, s8, 0
	v_mbcnt_hi_u32_b32 v1, s9, v1
	v_cmp_eq_u32_e32 vcc, 0, v1
	s_waitcnt vmcnt(0)
	buffer_inv sc1
	s_and_saveexec_b64 s[10:11], vcc
	s_cbranch_execz .LBB0_488
	s_bcnt1_i32_b64 s3, s[8:9]
	v_mov_b32_e32 v1, 0x2000
	v_mov_b32_e32 v2, s3
.LBB0_488:
	s_or_b64 exec, exec, s[10:11]
	s_waitcnt vmcnt(0)

.LBB0_556:
	s_or_b64 exec, exec, s[8:9]
	s_mov_b64 s[8:9], exec
	v_mbcnt_lo_u32_b32 v1, s8, 0
	v_mbcnt_hi_u32_b32 v1, s9, v1
	v_cmp_eq_u32_e32 vcc, 0, v1
	s_waitcnt vmcnt(0)
	buffer_inv sc1
	s_and_saveexec_b64 s[10:11], vcc
	s_cbranch_execz .LBB0_558
	s_bcnt1_i32_b64 s3, s[8:9]
	v_mov_b32_e32 v1, 0x2000
	v_mov_b32_e32 v2, s3
.LBB0_558:
	s_or_b64 exec, exec, s[10:11]
	s_waitcnt vmcnt(0)

.LBB0_647:
	s_or_b64 exec, exec, s[8:9]
	s_mov_b64 s[8:9], exec
	v_mbcnt_lo_u32_b32 v1, s8, 0
	v_mbcnt_hi_u32_b32 v1, s9, v1
	v_cmp_eq_u32_e32 vcc, 0, v1
	s_waitcnt vmcnt(0)
	buffer_inv sc1
	s_and_saveexec_b64 s[10:11], vcc
	s_cbranch_execz .LBB0_649
	s_bcnt1_i32_b64 s3, s[8:9]
	v_mov_b32_e32 v1, 0x2000
	v_mov_b32_e32 v2, s3
.LBB0_649:
	s_or_b64 exec, exec, s[10:11]
	s_waitcnt vmcnt(0)

.LBB0_886:
	s_or_b64 exec, exec, s[8:9]
	s_mov_b64 s[8:9], exec
	v_mbcnt_lo_u32_b32 v1, s8, 0
	v_mbcnt_hi_u32_b32 v1, s9, v1
	v_cmp_eq_u32_e32 vcc, 0, v1
	s_waitcnt vmcnt(0)
	buffer_inv sc1
	s_and_saveexec_b64 s[10:11], vcc
	s_cbranch_execz .LBB0_888
	s_bcnt1_i32_b64 s3, s[8:9]
	v_mov_b32_e32 v1, 0x2000
	v_mov_b32_e32 v2, s3
.LBB0_888:
	s_or_b64 exec, exec, s[10:11]
	s_waitcnt vmcnt(0)

.LBB0_964:
	s_or_b64 exec, exec, s[8:9]
	s_mov_b64 s[8:9], exec
	v_mbcnt_lo_u32_b32 v1, s8, 0
	v_mbcnt_hi_u32_b32 v1, s9, v1
	v_cmp_eq_u32_e32 vcc, 0, v1
	s_waitcnt vmcnt(0)
	buffer_inv sc1
	s_and_saveexec_b64 s[10:11], vcc
	s_cbranch_execz .LBB0_966
	s_bcnt1_i32_b64 s3, s[8:9]
	v_mov_b32_e32 v1, 0x2000
	v_mov_b32_e32 v2, s3
.LBB0_966:
	s_or_b64 exec, exec, s[10:11]
	s_waitcnt vmcnt(0)

.LBB0_1057:
	s_or_b64 exec, exec, s[8:9]
	s_mov_b64 s[8:9], exec
	v_mbcnt_lo_u32_b32 v1, s8, 0
	v_mbcnt_hi_u32_b32 v1, s9, v1
	v_cmp_eq_u32_e32 vcc, 0, v1
	s_waitcnt vmcnt(0)
	buffer_inv sc1
	s_and_saveexec_b64 s[10:11], vcc
	s_cbranch_execz .LBB0_1059
	s_bcnt1_i32_b64 s3, s[8:9]
	v_mov_b32_e32 v1, 0x2000
	v_mov_b32_e32 v2, s3
.LBB0_1059:
	s_or_b64 exec, exec, s[10:11]
	s_waitcnt vmcnt(0)

.LBB0_1127:
	s_or_b64 exec, exec, s[8:9]
	s_mov_b64 s[8:9], exec
	v_mbcnt_lo_u32_b32 v1, s8, 0
	v_mbcnt_hi_u32_b32 v1, s9, v1
	v_cmp_eq_u32_e32 vcc, 0, v1
	s_waitcnt vmcnt(0)
	buffer_inv sc1
	s_and_saveexec_b64 s[10:11], vcc
	s_cbranch_execz .LBB0_1129
	s_bcnt1_i32_b64 s3, s[8:9]
	v_mov_b32_e32 v1, 0x2000
	v_mov_b32_e32 v2, s3
.LBB0_1129:
	s_or_b64 exec, exec, s[10:11]
	s_waitcnt vmcnt(0)

.LBB0_1217:
	s_or_b64 exec, exec, s[8:9]
	s_mov_b64 s[8:9], exec
	v_mbcnt_lo_u32_b32 v1, s8, 0
	v_mbcnt_hi_u32_b32 v1, s9, v1
	v_cmp_eq_u32_e32 vcc, 0, v1
	s_waitcnt vmcnt(0)
	buffer_inv sc1
	s_and_saveexec_b64 s[10:11], vcc
	s_cbranch_execz .LBB0_1219
	s_bcnt1_i32_b64 s3, s[8:9]
	v_mov_b32_e32 v1, 0x2000
	v_mov_b32_e32 v2, s3
.LBB0_1219:
	s_or_b64 exec, exec, s[10:11]
	s_waitcnt vmcnt(0)

.LBB0_1279:
	s_or_b64 exec, exec, s[10:11]
	v_cvt_f32_u32_e32 v4, v2
	s_waitcnt vmcnt(0)
	v_readfirstlane_b32 s3, v3
	v_sub_u32_e32 v3, 0, v2
	v_rcp_iflag_f32_e32 v4, v4
	v_add_u32_e32 v5, s3, v1
	v_mul_f32_e32 v4, 0x4f7ffffe, v4
	v_cvt_u32_f32_e32 v4, v4
	v_mul_lo_u32 v1, v3, v4
	v_mul_hi_u32 v1, v4, v1
	v_add_u32_e32 v1, v4, v1
	v_mul_hi_u32 v1, v5, v1
	v_mul_lo_u32 v3, v1, v2
	v_sub_u32_e32 v3, v5, v3
	v_add_u32_e32 v4, 1, v1
	v_cmp_ge_u32_e32 vcc, v3, v2
	s_nop 1
	v_cndmask_b32_e32 v1, v1, v4, vcc
	v_sub_u32_e32 v4, v3, v2
	v_cndmask_b32_e32 v3, v3, v4, vcc
	v_add_u32_e32 v4, 1, v1
	v_cmp_ge_u32_e32 vcc, v3, v2
	v_add_u32_e32 v3, 1, v5
	s_nop 0
	v_cndmask_b32_e32 v1, v1, v4, vcc
	v_mul_lo_u32 v4, v2, v1
	v_add_u32_e32 v2, v4, v2
	v_cmp_ne_u32_e32 vcc, v3, v2
	s_and_saveexec_b64 s[8:9], vcc
	s_xor_b64 s[8:9], exec, s[8:9]
	s_cbranch_execz .LBB0_1293
	s_waitcnt lgkmcnt(0)
	v_mov_b32_e32 v0, 0x23903500
	global_load_dword v0, v0, s[26:27] sc1
	s_add_u32 s14, s26, 0x23903500
	s_addc_u32 s15, s27, 0
	s_waitcnt vmcnt(0)
	v_cmp_eq_u32_e32 vcc, v0, v1
	s_and_saveexec_b64 s[10:11], vcc
	s_cbranch_execz .LBB0_1292
	s_add_u32 s12, s26, 0x23900200
	s_addc_u32 s13, s27, 0
	s_mov_b32 s3, 1
	s_mov_b64 s[16:17], 0
	v_mov_b32_e32 v0, 0
	s_branch .LBB0_1283

.LBB0_1310:
	s_or_b64 exec, exec, s[8:9]
	s_mov_b64 s[8:9], exec
	v_mbcnt_lo_u32_b32 v0, s8, 0
	v_mbcnt_hi_u32_b32 v0, s9, v0
	v_cmp_eq_u32_e32 vcc, 0, v0
	s_waitcnt vmcnt(0)
	buffer_inv sc1
	s_and_saveexec_b64 s[10:11], vcc
	s_cbranch_execz .LBB0_1312
	s_bcnt1_i32_b64 s3, s[8:9]
	v_mov_b32_e32 v0, 0x2000
	v_mov_b32_e32 v1, s3
.LBB0_1312:
	s_or_b64 exec, exec, s[10:11]
	s_waitcnt vmcnt(0)
